# input projection and gate/up GEMM: first two K-loop waits of a tile let the previous tile's result stores stay in flight (vmcnt 24 / 16)
# speedup vs baseline: 1.0029x; 1.0029x over previous
.LBB0_224:
	s_or_b64 exec, exec, s[0:1]
	s_mov_b32 s101, 0
	s_add_u32 s18, s90, 0x48f0000
	s_addc_u32 s19, s91, 0
	s_add_u32 s48, s90, 0x60000
	s_addc_u32 s49, s91, 0
	v_mov_b32_e32 v8, v193
	s_cmpk_lt_i32 s6, 0x800
	s_waitcnt lgkmcnt(0)
	s_barrier
	s_cselect_b64 s[0:1], -1, 0
	s_cmpk_gt_i32 s6, 0x7ff
	v_readfirstlane_b32 s2, v8
	s_cbranch_scc1 .LBB0_227
	s_ashr_i32 s3, s6, 31
	s_lshr_b32 s3, s3, 29
	s_add_i32 s3, s6, s3
	s_and_b32 s4, s3, -8
	s_sub_i32 s7, s6, s4
	s_cmp_gt_i32 s7, -1
	s_cbranch_scc0 .LBB0_228
	s_lshl_b32 s8, s7, 8
	s_cbranch_execz .LBB0_229
	s_branch .LBB0_230

.LBB0_244:
	ds_read_b128 v[146:149], v161
	ds_read_b128 v[150:153], v161 offset:1024
	ds_read_b128 v[154:157], v161 offset:2048
	ds_read_b128 v[164:167], v161 offset:3072
	ds_read_b128 v[168:171], v162
	ds_read_b128 v[172:175], v162 offset:1024
	ds_read_b128 v[176:179], v162 offset:2048
	ds_read_b128 v[180:183], v162 offset:3072
	s_add_u32 s7, s40, 0xfffc0080
	s_addc_u32 s9, s41, -1
	s_cmp_eq_u32 s5, 12
	s_cselect_b32 s45, s29, s9
	s_cselect_b32 s44, s28, s7
	s_cselect_b32 s43, s39, s3
	s_cselect_b32 s42, s38, s2
	v_lshl_add_u64 v[218:219], s[40:41], 0, v[138:139]
	s_add_i32 m0, s51, 0xc000
	ds_read_b128 v[184:187], v163
	ds_read_b128 v[188:191], v163 offset:1024
	ds_read_b128 v[194:197], v163 offset:2048
	ds_read_b128 v[198:201], v163 offset:3072
	ds_read_b128 v[202:205], v163 offset:4096
	ds_read_b128 v[206:209], v163 offset:5120
	ds_read_b128 v[210:213], v163 offset:6144
	ds_read_b128 v[214:217], v163 offset:7168
	global_load_lds_dwordx4 v[218:219], off
	v_lshl_add_u64 v[218:219], s[40:41], 0, v[140:141]
	s_add_i32 m0, s51, 0xe000
	s_nop 0
	global_load_lds_dwordx4 v[218:219], off
	s_cmp_eq_u32 s101, 0
	s_cbranch_scc1 .Lxw_p2_1s
	s_waitcnt vmcnt(24)
	s_branch .Lxw_p2_1j

.Lxw_p2_1j:
	s_waitcnt lgkmcnt(0)
	s_barrier
	s_setprio 1
	s_waitcnt lgkmcnt(0)
	v_mfma_f32_16x16x32_bf16 v[124:127], v[146:149], v[184:187], v[124:127]
	v_mfma_f32_16x16x32_bf16 v[120:123], v[154:157], v[184:187], v[120:123]
	v_mfma_f32_16x16x32_bf16 v[108:111], v[146:149], v[194:197], v[108:111]
	v_mfma_f32_16x16x32_bf16 v[104:107], v[154:157], v[194:197], v[104:107]
	v_mfma_f32_16x16x32_bf16 v[92:95], v[146:149], v[202:205], v[92:95]
	v_mfma_f32_16x16x32_bf16 v[88:91], v[154:157], v[202:205], v[88:91]
	v_mfma_f32_16x16x32_bf16 v[76:79], v[146:149], v[210:213], v[76:79]
	v_mfma_f32_16x16x32_bf16 v[72:75], v[154:157], v[210:213], v[72:75]
	v_mfma_f32_16x16x32_bf16 v[124:127], v[150:153], v[188:191], v[124:127]
	v_mfma_f32_16x16x32_bf16 v[120:123], v[164:167], v[188:191], v[120:123]
	v_mfma_f32_16x16x32_bf16 v[108:111], v[150:153], v[198:201], v[108:111]
	v_mfma_f32_16x16x32_bf16 v[104:107], v[164:167], v[198:201], v[104:107]
	v_mfma_f32_16x16x32_bf16 v[92:95], v[150:153], v[206:209], v[92:95]
	v_mfma_f32_16x16x32_bf16 v[88:91], v[164:167], v[206:209], v[88:91]
	v_mfma_f32_16x16x32_bf16 v[76:79], v[150:153], v[214:217], v[76:79]
	v_mfma_f32_16x16x32_bf16 v[72:75], v[164:167], v[214:217], v[72:75]
	v_mfma_f32_16x16x32_bf16 v[116:119], v[168:171], v[184:187], v[116:119]
	v_mfma_f32_16x16x32_bf16 v[112:115], v[176:179], v[184:187], v[112:115]
	v_mfma_f32_16x16x32_bf16 v[100:103], v[168:171], v[194:197], v[100:103]
	v_mfma_f32_16x16x32_bf16 v[96:99], v[176:179], v[194:197], v[96:99]
	v_mfma_f32_16x16x32_bf16 v[84:87], v[168:171], v[202:205], v[84:87]
	v_mfma_f32_16x16x32_bf16 v[80:83], v[176:179], v[202:205], v[80:83]
	v_mfma_f32_16x16x32_bf16 v[68:71], v[168:171], v[210:213], v[68:71]
	v_mfma_f32_16x16x32_bf16 v[64:67], v[176:179], v[210:213], v[64:67]
	v_mfma_f32_16x16x32_bf16 v[116:119], v[172:175], v[188:191], v[116:119]
	v_mfma_f32_16x16x32_bf16 v[112:115], v[180:183], v[188:191], v[112:115]
	v_mfma_f32_16x16x32_bf16 v[100:103], v[172:175], v[198:201], v[100:103]
	v_mfma_f32_16x16x32_bf16 v[96:99], v[180:183], v[198:201], v[96:99]
	v_mfma_f32_16x16x32_bf16 v[84:87], v[172:175], v[206:209], v[84:87]
	v_mfma_f32_16x16x32_bf16 v[80:83], v[180:183], v[206:209], v[80:83]
	v_mfma_f32_16x16x32_bf16 v[68:71], v[172:175], v[214:217], v[68:71]
	v_mfma_f32_16x16x32_bf16 v[64:67], v[180:183], v[214:217], v[64:67]
	s_setprio 0
	s_barrier
	s_add_i32 s7, s68, s50
	v_lshl_add_u64 v[218:219], s[42:43], 0, v[130:131]
	s_mov_b32 m0, s7
	ds_read_b128 v[184:187], v163 offset:16384
	ds_read_b128 v[188:191], v163 offset:17408
	ds_read_b128 v[194:197], v163 offset:18432
	ds_read_b128 v[198:201], v163 offset:19456
	ds_read_b128 v[202:205], v163 offset:20480
	ds_read_b128 v[206:209], v163 offset:21504
	ds_read_b128 v[210:213], v163 offset:22528
	ds_read_b128 v[214:217], v163 offset:23552
	global_load_lds_dwordx4 v[218:219], off
	s_add_i32 m0, s7, 0x2000
	s_add_u32 s34, s42, 0x40000
	v_lshl_add_u64 v[220:221], s[42:43], 0, v[134:135]
	s_addc_u32 s35, s43, 0
	s_add_i32 s7, s69, s50
	global_load_lds_dwordx4 v[220:221], off
	v_lshl_add_u64 v[222:223], s[34:35], 0, v[130:131]
	s_mov_b32 m0, s7
	v_lshl_add_u64 v[224:225], s[44:45], 0, v[132:133]
	global_load_lds_dwordx4 v[222:223], off
	v_lshl_add_u64 v[222:223], s[34:35], 0, v[134:135]
	s_add_i32 m0, s7, 0x2000
	s_nop 0
	global_load_lds_dwordx4 v[222:223], off
	v_lshl_add_u64 v[222:223], s[44:45], 0, v[128:129]
	s_mov_b32 m0, s51
	s_nop 0
	global_load_lds_dwordx4 v[222:223], off
	s_mov_b32 m0, s58
	s_nop 0
	global_load_lds_dwordx4 v[224:225], off
	s_cmp_eq_u32 s101, 0
	s_cbranch_scc1 .Lxw_p2_2s
	s_waitcnt vmcnt(24)
	s_mov_b32 s101, 0
	s_branch .Lxw_p2_2j

.Lxw_p2_2j:
	s_waitcnt lgkmcnt(0)
	s_barrier
	s_setprio 1
	s_waitcnt lgkmcnt(0)
	v_mfma_f32_16x16x32_bf16 v[60:63], v[146:149], v[184:187], v[60:63]
	v_mfma_f32_16x16x32_bf16 v[56:59], v[154:157], v[184:187], v[56:59]
	v_mfma_f32_16x16x32_bf16 v[44:47], v[146:149], v[194:197], v[44:47]
	v_mfma_f32_16x16x32_bf16 v[40:43], v[154:157], v[194:197], v[40:43]
	v_mfma_f32_16x16x32_bf16 v[28:31], v[146:149], v[202:205], v[28:31]
	v_mfma_f32_16x16x32_bf16 v[24:27], v[154:157], v[202:205], v[24:27]
	v_mfma_f32_16x16x32_bf16 v[12:15], v[146:149], v[210:213], v[12:15]
	v_mfma_f32_16x16x32_bf16 v[8:11], v[154:157], v[210:213], v[8:11]
	v_mfma_f32_16x16x32_bf16 v[60:63], v[150:153], v[188:191], v[60:63]
	v_mfma_f32_16x16x32_bf16 v[56:59], v[164:167], v[188:191], v[56:59]
	v_mfma_f32_16x16x32_bf16 v[44:47], v[150:153], v[198:201], v[44:47]
	v_mfma_f32_16x16x32_bf16 v[40:43], v[164:167], v[198:201], v[40:43]
	v_mfma_f32_16x16x32_bf16 v[28:31], v[150:153], v[206:209], v[28:31]
	v_mfma_f32_16x16x32_bf16 v[24:27], v[164:167], v[206:209], v[24:27]
	v_mfma_f32_16x16x32_bf16 v[12:15], v[150:153], v[214:217], v[12:15]
	v_mfma_f32_16x16x32_bf16 v[8:11], v[164:167], v[214:217], v[8:11]
	v_mfma_f32_16x16x32_bf16 v[52:55], v[168:171], v[184:187], v[52:55]
	v_mfma_f32_16x16x32_bf16 v[48:51], v[176:179], v[184:187], v[48:51]
	v_mfma_f32_16x16x32_bf16 v[36:39], v[168:171], v[194:197], v[36:39]
	v_mfma_f32_16x16x32_bf16 v[32:35], v[176:179], v[194:197], v[32:35]
	v_mfma_f32_16x16x32_bf16 v[20:23], v[168:171], v[202:205], v[20:23]
	v_mfma_f32_16x16x32_bf16 v[16:19], v[176:179], v[202:205], v[16:19]
	v_mfma_f32_16x16x32_bf16 v[4:7], v[168:171], v[210:213], v[4:7]
	v_mfma_f32_16x16x32_bf16 v[0:3], v[176:179], v[210:213], v[0:3]
	v_mfma_f32_16x16x32_bf16 v[52:55], v[172:175], v[188:191], v[52:55]
	v_mfma_f32_16x16x32_bf16 v[48:51], v[180:183], v[188:191], v[48:51]
	v_mfma_f32_16x16x32_bf16 v[36:39], v[172:175], v[198:201], v[36:39]
	v_mfma_f32_16x16x32_bf16 v[32:35], v[180:183], v[198:201], v[32:35]
	v_mfma_f32_16x16x32_bf16 v[20:23], v[172:175], v[206:209], v[20:23]
	v_mfma_f32_16x16x32_bf16 v[16:19], v[180:183], v[206:209], v[16:19]
	v_mfma_f32_16x16x32_bf16 v[4:7], v[172:175], v[214:217], v[4:7]
	v_mfma_f32_16x16x32_bf16 v[0:3], v[180:183], v[214:217], v[0:3]
	s_setprio 0
	s_barrier
	s_add_i32 s7, 0, 0x18000
	v_add_u32_e32 v136, s7, v159
	s_add_i32 s9, 0, 0x1c000
	ds_read_b128 v[146:149], v136
	ds_read_b128 v[150:153], v136 offset:1024
	ds_read_b128 v[154:157], v136 offset:2048
	ds_read_b128 v[164:167], v136 offset:3072
	v_add_u32_e32 v136, s9, v159
	ds_read_b128 v[168:171], v136
	ds_read_b128 v[172:175], v136 offset:1024
	ds_read_b128 v[176:179], v136 offset:2048
	ds_read_b128 v[180:183], v136 offset:3072
	s_add_u32 s34, s44, 0x40000
	s_addc_u32 s35, s45, 0
	s_mov_b32 m0, s59
	v_lshl_add_u64 v[228:229], s[34:35], 0, v[128:129]
	ds_read_b128 v[184:187], v163 offset:32768
	ds_read_b128 v[188:191], v163 offset:33792
	ds_read_b128 v[194:197], v163 offset:34816
	ds_read_b128 v[198:201], v163 offset:35840
	ds_read_b128 v[202:205], v163 offset:36864
	ds_read_b128 v[206:209], v163 offset:37888
	ds_read_b128 v[210:213], v163 offset:38912
	ds_read_b128 v[214:217], v163 offset:39936
	global_load_lds_dwordx4 v[228:229], off
	v_lshl_add_u64 v[228:229], s[34:35], 0, v[132:133]
	s_mov_b32 m0, s60
	s_nop 0
	global_load_lds_dwordx4 v[228:229], off
	s_waitcnt vmcnt(8)
	s_waitcnt lgkmcnt(0)
	s_barrier
	s_setprio 1
	s_waitcnt lgkmcnt(0)
	v_mfma_f32_16x16x32_bf16 v[124:127], v[146:149], v[184:187], v[124:127]
	v_mfma_f32_16x16x32_bf16 v[120:123], v[154:157], v[184:187], v[120:123]
	v_mfma_f32_16x16x32_bf16 v[108:111], v[146:149], v[194:197], v[108:111]
	v_mfma_f32_16x16x32_bf16 v[104:107], v[154:157], v[194:197], v[104:107]
	v_mfma_f32_16x16x32_bf16 v[92:95], v[146:149], v[202:205], v[92:95]
	v_mfma_f32_16x16x32_bf16 v[88:91], v[154:157], v[202:205], v[88:91]
	v_mfma_f32_16x16x32_bf16 v[76:79], v[146:149], v[210:213], v[76:79]
	v_mfma_f32_16x16x32_bf16 v[72:75], v[154:157], v[210:213], v[72:75]
	v_mfma_f32_16x16x32_bf16 v[124:127], v[150:153], v[188:191], v[124:127]
	v_mfma_f32_16x16x32_bf16 v[120:123], v[164:167], v[188:191], v[120:123]
	v_mfma_f32_16x16x32_bf16 v[108:111], v[150:153], v[198:201], v[108:111]
	v_mfma_f32_16x16x32_bf16 v[104:107], v[164:167], v[198:201], v[104:107]
	v_mfma_f32_16x16x32_bf16 v[92:95], v[150:153], v[206:209], v[92:95]
	v_mfma_f32_16x16x32_bf16 v[88:91], v[164:167], v[206:209], v[88:91]
	v_mfma_f32_16x16x32_bf16 v[76:79], v[150:153], v[214:217], v[76:79]
	v_mfma_f32_16x16x32_bf16 v[72:75], v[164:167], v[214:217], v[72:75]
	v_mfma_f32_16x16x32_bf16 v[116:119], v[168:171], v[184:187], v[116:119]
	v_mfma_f32_16x16x32_bf16 v[112:115], v[176:179], v[184:187], v[112:115]
	v_mfma_f32_16x16x32_bf16 v[100:103], v[168:171], v[194:197], v[100:103]
	v_mfma_f32_16x16x32_bf16 v[96:99], v[176:179], v[194:197], v[96:99]
	v_mfma_f32_16x16x32_bf16 v[84:87], v[168:171], v[202:205], v[84:87]
	v_mfma_f32_16x16x32_bf16 v[80:83], v[176:179], v[202:205], v[80:83]
	v_mfma_f32_16x16x32_bf16 v[68:71], v[168:171], v[210:213], v[68:71]
	v_mfma_f32_16x16x32_bf16 v[64:67], v[176:179], v[210:213], v[64:67]
	v_mfma_f32_16x16x32_bf16 v[116:119], v[172:175], v[188:191], v[116:119]
	v_mfma_f32_16x16x32_bf16 v[112:115], v[180:183], v[188:191], v[112:115]
	v_mfma_f32_16x16x32_bf16 v[100:103], v[172:175], v[198:201], v[100:103]
	v_mfma_f32_16x16x32_bf16 v[96:99], v[180:183], v[198:201], v[96:99]
	v_mfma_f32_16x16x32_bf16 v[84:87], v[172:175], v[206:209], v[84:87]
	v_mfma_f32_16x16x32_bf16 v[80:83], v[180:183], v[206:209], v[80:83]
	v_mfma_f32_16x16x32_bf16 v[68:71], v[172:175], v[214:217], v[68:71]
	v_mfma_f32_16x16x32_bf16 v[64:67], v[180:183], v[214:217], v[64:67]
	s_setprio 0
	s_barrier
	s_add_i32 s7, s7, s50
	v_lshl_add_u64 v[218:219], v[218:219], 0, s[12:13]
	s_mov_b32 m0, s7
	ds_read_b128 v[184:187], v163 offset:49152
	ds_read_b128 v[188:191], v163 offset:50176
	ds_read_b128 v[194:197], v163 offset:51200
	ds_read_b128 v[198:201], v163 offset:52224
	ds_read_b128 v[202:205], v163 offset:53248
	ds_read_b128 v[206:209], v163 offset:54272
	ds_read_b128 v[210:213], v163 offset:55296
	ds_read_b128 v[214:217], v163 offset:56320
	global_load_lds_dwordx4 v[218:219], off
	s_add_i32 m0, s7, 0x2000
	s_add_u32 s34, s42, 0x40080
	v_lshl_add_u64 v[218:219], v[220:221], 0, s[12:13]
	s_addc_u32 s35, s43, 0
	s_add_i32 s7, s9, s50
	global_load_lds_dwordx4 v[218:219], off
	v_lshl_add_u64 v[218:219], s[34:35], 0, v[130:131]
	s_mov_b32 m0, s7
	s_nop 0
	global_load_lds_dwordx4 v[218:219], off
	v_lshl_add_u64 v[218:219], s[34:35], 0, v[134:135]
	s_add_i32 m0, s7, 0x2000
	s_nop 0
	global_load_lds_dwordx4 v[218:219], off
	v_lshl_add_u64 v[218:219], v[222:223], 0, s[12:13]
	s_mov_b32 m0, s63
	s_nop 0
	global_load_lds_dwordx4 v[218:219], off
	v_lshl_add_u64 v[218:219], v[224:225], 0, s[12:13]
	s_mov_b32 m0, s64
	s_nop 0
	global_load_lds_dwordx4 v[218:219], off
	s_waitcnt vmcnt(8)
	s_waitcnt lgkmcnt(0)
	s_barrier
	s_setprio 1
	s_waitcnt lgkmcnt(0)
	v_mfma_f32_16x16x32_bf16 v[60:63], v[146:149], v[184:187], v[60:63]
	v_mfma_f32_16x16x32_bf16 v[56:59], v[154:157], v[184:187], v[56:59]
	v_mfma_f32_16x16x32_bf16 v[44:47], v[146:149], v[194:197], v[44:47]
	v_mfma_f32_16x16x32_bf16 v[40:43], v[154:157], v[194:197], v[40:43]
	v_mfma_f32_16x16x32_bf16 v[28:31], v[146:149], v[202:205], v[28:31]
	v_mfma_f32_16x16x32_bf16 v[24:27], v[154:157], v[202:205], v[24:27]
	v_mfma_f32_16x16x32_bf16 v[12:15], v[146:149], v[210:213], v[12:15]
	v_mfma_f32_16x16x32_bf16 v[8:11], v[154:157], v[210:213], v[8:11]
	v_mfma_f32_16x16x32_bf16 v[60:63], v[150:153], v[188:191], v[60:63]
	v_mfma_f32_16x16x32_bf16 v[56:59], v[164:167], v[188:191], v[56:59]
	v_mfma_f32_16x16x32_bf16 v[44:47], v[150:153], v[198:201], v[44:47]
	v_mfma_f32_16x16x32_bf16 v[40:43], v[164:167], v[198:201], v[40:43]
	v_mfma_f32_16x16x32_bf16 v[28:31], v[150:153], v[206:209], v[28:31]
	v_mfma_f32_16x16x32_bf16 v[24:27], v[164:167], v[206:209], v[24:27]
	v_mfma_f32_16x16x32_bf16 v[12:15], v[150:153], v[214:217], v[12:15]
	v_mfma_f32_16x16x32_bf16 v[8:11], v[164:167], v[214:217], v[8:11]
	v_mfma_f32_16x16x32_bf16 v[52:55], v[168:171], v[184:187], v[52:55]
	v_mfma_f32_16x16x32_bf16 v[48:51], v[176:179], v[184:187], v[48:51]
	v_mfma_f32_16x16x32_bf16 v[36:39], v[168:171], v[194:197], v[36:39]
	v_mfma_f32_16x16x32_bf16 v[32:35], v[176:179], v[194:197], v[32:35]
	v_mfma_f32_16x16x32_bf16 v[20:23], v[168:171], v[202:205], v[20:23]
	v_mfma_f32_16x16x32_bf16 v[16:19], v[176:179], v[202:205], v[16:19]
	v_mfma_f32_16x16x32_bf16 v[4:7], v[168:171], v[210:213], v[4:7]
	v_mfma_f32_16x16x32_bf16 v[0:3], v[176:179], v[210:213], v[0:3]
	v_mfma_f32_16x16x32_bf16 v[52:55], v[172:175], v[188:191], v[52:55]
	v_mfma_f32_16x16x32_bf16 v[48:51], v[180:183], v[188:191], v[48:51]
	v_mfma_f32_16x16x32_bf16 v[36:39], v[172:175], v[198:201], v[36:39]
	v_mfma_f32_16x16x32_bf16 v[32:35], v[180:183], v[198:201], v[32:35]
	v_mfma_f32_16x16x32_bf16 v[20:23], v[172:175], v[206:209], v[20:23]
	v_mfma_f32_16x16x32_bf16 v[16:19], v[180:183], v[206:209], v[16:19]
	v_mfma_f32_16x16x32_bf16 v[4:7], v[172:175], v[214:217], v[4:7]
	v_mfma_f32_16x16x32_bf16 v[0:3], v[180:183], v[214:217], v[0:3]
	s_setprio 0
	s_barrier
	s_add_i32 s5, s5, 2
	s_add_u32 s40, s40, 0x100
	s_addc_u32 s41, s41, 0
	s_add_u32 s2, s2, 0x100
	s_addc_u32 s3, s3, 0
	s_cmp_gt_u32 s5, 13
	s_cbranch_scc0 .LBB0_244
	s_and_b64 vcc, exec, s[14:15]
	s_cbranch_vccz .LBB0_247
	s_barrier

.Luhy_join:
	s_mov_b32 s101, 1
	s_mov_b64 s[4:5], -1
	s_and_b64 vcc, exec, s[0:1]
	s_cbranch_vccz .LBB0_236
